# v15 + attention: at each call's loop exit, one-dword loads touch the next call's first K/V tiles, rope-K rows and Q rows (L2 warm-up)
# speedup vs baseline: 1.0002x; 1.0002x over previous
; __device__ __forceinline__ void phase_attn_mla(const Params& p, char* lds) {
;     ...
;     for (int it = blockIdx.x; it < 1024 + 128; it += gridDim.x) {
;         int b, h, row0; AttnArgs a;
;         if (it < 1024) {
;             int itm = it;
;             if (gridDim.x == 256) { const int w = it & 255, rnd = it >> 8, xcd = w & 7, slot = w >> 3; itm = ((rnd * 32 + xcd * 4 + (slot >> 3)) << 3) | (slot & 7); }
;             b = itm >> 6; h = (itm >> 3) & 7; const int qb = itm & 7; row0 = b * SEQ + qb * 256; a.nlat = 32; a.NT = 36; }
;         else { const int i2 = it - 1024; b = i2 >> 3; h = i2 & 7; row0 = MLAT + b * CTXL; a.nlat = 0; a.NT = 4; }
;         a.lat0 = b * SEQ; a.ctx0 = MLAT + b * CTXL;
;         a.Q = T1 + T_Q + (size_t)row0 * 1536 + h * 192; a.ldq = 1536;
;         a.Kn = T1 + T_KV + h * 256; a.ldk = 2048; a.Kr = T1 + T_KR; a.ldkr = 64;
;         a.V = T1 + T_KV + h * 256 + 128; a.ldv = 2048;
; __device__ __forceinline__ void phase_attn_diff(const Params& p, char* lds) {
;     ...
;     for (int it = blockIdx.x; it < 1024; it += gridDim.x) {
;         int itm = it;
;         if (gridDim.x == 256) { const int w = it & 255, rnd = it >> 8, xcd = w & 7, slot = w >> 3; itm = ((rnd * 32 + xcd * 4 + (slot >> 3)) << 3) | (slot & 7); }
;         const int b = itm >> 6, h = (itm >> 3) & 7, qb = itm & 7, row0 = b * SEQ + qb * 256;
; #pragma unroll 1
;         for (int j = 0; j < 2; ++j) {
;             AttnArgs a; a.nlat = 32; a.NT = 36; a.lat0 = b * SEQ; a.ctx0 = MLAT + b * CTXL;
;             a.Q = T1 + (size_t)row0 * 3072 + h * 128 + j * 64; a.ldq = 3072;
;             a.Kn = T1 + 1024 + h * 128 + j * 64; a.ldk = 3072; a.Kr = a.Kn; a.ldkr = 3072;
;             a.V = T1 + 2048 + h * 128; a.ldv = 3072;
.LBB0_183:
	s_and_b64 s[14:15], s[94:95], exec
	s_cselect_b32 s98, s56, 0
	s_cselect_b32 s99, 0, 0x80
	s_add_i32 s98, s85, s98
	s_cmpk_gt_i32 s98, 0x3ff
	s_cbranch_scc1 .Lwd_skip
	s_lshl_b32 s14, s98, 5
	s_and_b32 s14, s14, 0xe0
	s_and_b32 s15, s98, 0xffffff00
	s_or_b32 s14, s14, s15
	s_bfe_u32 s15, s98, 0x50003
	s_or_b32 s14, s14, s15
	s_and_b64 s[38:39], s[16:17], exec
	s_cselect_b32 s98, s14, s98
	s_ashr_i32 s14, s98, 6
	s_lshl_b32 s14, s14, 11
	s_lshl_b32 s15, s98, 8
	s_and_b32 s15, s15, 0x700
	s_or_b32 s15, s14, s15
	s_lshl_b32 s98, s98, 5
	s_and_b32 s98, s98, 0x700
	s_mul_i32 s14, s14, 0x1800
	s_add_u32 s14, s14, s98
	s_add_u32 s38, s4, s14
	s_addc_u32 s39, s5, 0
	v_and_b32_e32 v238, 0x7f, v159
	v_mul_u32_u24_e32 v238, 0x1800, v238
	v_lshrrev_b32_e32 v239, 7, v159
	v_mul_u32_u24_e32 v240, 0x80, v239
	v_add_u32_e32 v240, 0xf80, v240
	v_mov_b32_e32 v241, s99
	v_add_u32_e32 v241, 0x800, v241
	v_add_u32_e32 v239, -1, v239
	v_cmp_gt_u32_e32 vcc, 2, v239
	s_nop 1
	v_cndmask_b32_e32 v240, v241, v240, vcc
	v_add_u32_e32 v238, v238, v240
	global_load_dword v242, v238, s[38:39]
	s_mul_i32 s15, s15, 0x1800
	s_add_u32 s15, s15, s98
	s_add_u32 s15, s15, s99
	s_add_u32 s38, s4, s15
	s_addc_u32 s39, s5, 0
	v_and_b32_e32 v238, 0xff, v159
	v_mul_u32_u24_e32 v238, 0x1800, v238
	global_load_dword v243, v238, s[38:39]

; #define SBAR() __builtin_amdgcn_sched_barrier(0)
; template <int DQK, int DK1, int LDQ, int LDK, int LDKR, int LDV, int NQL, int SDEPTH>
; __device__ __forceinline__ void attn_core(const AttnArgs& a, char* lds, f32x16 (&o)[4]) {
;     ...
;     SBAR(); QKT(pB0, pB1, K_lds + SHM_K);
; __device__ __forceinline__ void phase_attn_mla(const Params& p, char* lds) {
;     ...
;     for (int it = blockIdx.x; it < 1024 + 128; it += gridDim.x) {
;         int b, h, row0; AttnArgs a;
;         if (it < 1024) {
;             int itm = it;
;             if (gridDim.x == 256) { const int w = it & 255, rnd = it >> 8, xcd = w & 7, slot = w >> 3; itm = ((rnd * 32 + xcd * 4 + (slot >> 3)) << 3) | (slot & 7); }
;             b = itm >> 6; h = (itm >> 3) & 7; const int qb = itm & 7; row0 = b * SEQ + qb * 256; a.nlat = 32; a.NT = 36; }
;         else { const int i2 = it - 1024; b = i2 >> 3; h = i2 & 7; row0 = MLAT + b * CTXL; a.nlat = 0; a.NT = 4; }
;         a.lat0 = b * SEQ; a.ctx0 = MLAT + b * CTXL;
;         a.Q = T1 + T_Q + (size_t)row0 * 1536 + h * 192; a.ldq = 1536;
;         a.Kn = T1 + T_KV + h * 256; a.ldk = 2048; a.Kr = T1 + T_KR; a.ldkr = 64;
;         a.V = T1 + T_KV + h * 256 + 128; a.ldv = 2048;
.LBB0_229:
	s_add_i32 s14, s25, 0x2000
	s_lshl_b32 s15, s14, 12
	s_lshl_b32 s20, s24, 9
	s_add_u32 s15, s15, s20
	s_add_u32 s20, s6, s15
	s_addc_u32 s21, s7, 0
	v_lshrrev_b32_e32 v248, 2, v159
	v_and_b32_e32 v249, 3, v159
	v_lshlrev_b32_e32 v248, 12, v248
	v_lshl_or_b32 v248, v249, 7, v248
	global_load_dword v250, v248, s[20:21]
	s_lshl_b32 s15, s14, 7
	s_add_u32 s20, s18, s15
	s_addc_u32 s21, s19, 0
	v_and_b32_e32 v249, 0x7f, v159
	v_lshlrev_b32_e32 v249, 7, v249
	global_load_dword v250, v249, s[20:21]
	s_add_i32 s14, s23, 0x2000
	s_mul_i32 s15, s14, 0xc00
	s_mul_i32 s20, s24, 0x180
	s_add_u32 s15, s15, s20
	s_add_u32 s20, s4, s15
	s_addc_u32 s21, s5, 0
	v_lshrrev_b32_e32 v248, 2, v159
	v_mul_u32_u24_e32 v248, 0xc00, v248
	v_and_b32_e32 v249, 3, v159
	v_lshl_or_b32 v248, v249, 7, v248
	global_load_dword v251, v248, s[20:21]
	s_add_u32 s20, s20, 0x60000
	s_addc_u32 s21, s21, 0
	global_load_dword v251, v248, s[20:21]
	ds_read_b128 v[64:67], v184 offset:57344
	ds_read_b128 v[68:71], v216 offset:12288
	s_waitcnt lgkmcnt(1)
	v_mfma_f32_32x32x16_bf16 v[80:95], v[64:67], v[126:129], 0
	s_waitcnt lgkmcnt(0)
	v_mfma_f32_32x32x16_bf16 v[64:79], v[68:71], v[126:129], 0
	ds_read_b128 v[126:129], v192 offset:57344
	ds_read_b128 v[174:177], v208 offset:12288
	s_waitcnt lgkmcnt(1)
	v_mfma_f32_32x32x16_bf16 v[80:95], v[126:129], v[122:125], v[80:95]
	s_waitcnt lgkmcnt(0)
	v_mfma_f32_32x32x16_bf16 v[64:79], v[174:177], v[122:125], v[64:79]
	ds_read_b128 v[122:125], v190 offset:57344
	ds_read_b128 v[126:129], v206 offset:12288
	s_waitcnt lgkmcnt(1)
	v_mfma_f32_32x32x16_bf16 v[80:95], v[122:125], v[118:121], v[80:95]
	s_waitcnt lgkmcnt(0)
	v_mfma_f32_32x32x16_bf16 v[64:79], v[126:129], v[118:121], v[64:79]
	ds_read_b128 v[118:121], v173 offset:57344
	ds_read_b128 v[122:125], v202 offset:12288
	s_waitcnt lgkmcnt(1)
	v_mfma_f32_32x32x16_bf16 v[80:95], v[118:121], v[114:117], v[80:95]
	s_waitcnt lgkmcnt(0)
	v_mfma_f32_32x32x16_bf16 v[64:79], v[122:125], v[114:117], v[64:79]
	ds_read_b128 v[114:117], v184 offset:57472
	ds_read_b128 v[118:121], v216 offset:12416
	v_exp_f32_e32 v122, v136
	v_exp_f32_e32 v123, v137
	s_waitcnt lgkmcnt(1)
	v_mfma_f32_32x32x16_bf16 v[80:95], v[114:117], v[110:113], v[80:95]
	s_waitcnt lgkmcnt(0)
	v_mfma_f32_32x32x16_bf16 v[64:79], v[118:121], v[110:113], v[64:79]
	ds_read_b128 v[110:113], v192 offset:57472
	ds_read_b128 v[114:117], v208 offset:12416
	v_exp_f32_e32 v118, v144
	v_exp_f32_e32 v119, v145
	v_exp_f32_e32 v120, v138
	v_exp_f32_e32 v121, v139
	s_waitcnt lgkmcnt(1)
	v_mfma_f32_32x32x16_bf16 v[80:95], v[110:113], v[106:109], v[80:95]
	s_waitcnt lgkmcnt(0)
	v_mfma_f32_32x32x16_bf16 v[64:79], v[114:117], v[106:109], v[64:79]
	ds_read_b128 v[106:109], v190 offset:57472
	ds_read_b128 v[110:113], v206 offset:12416
	v_exp_f32_e32 v114, v132
	v_exp_f32_e32 v115, v133
	v_exp_f32_e32 v116, v130
	v_exp_f32_e32 v117, v131
	s_waitcnt lgkmcnt(1)
	v_mfma_f32_32x32x16_bf16 v[80:95], v[106:109], v[102:105], v[80:95]
	s_waitcnt lgkmcnt(0)
	v_mfma_f32_32x32x16_bf16 v[64:79], v[110:113], v[102:105], v[64:79]
	ds_read_b128 v[102:105], v173 offset:57472
	ds_read_b128 v[106:109], v202 offset:12416
	v_exp_f32_e32 v110, v140
	v_exp_f32_e32 v111, v141
	v_exp_f32_e32 v112, v134
	v_exp_f32_e32 v113, v135
	s_waitcnt lgkmcnt(1)
	v_mfma_f32_32x32x16_bf16 v[80:95], v[102:105], v[98:101], v[80:95]
	s_waitcnt lgkmcnt(0)
	v_mfma_f32_32x32x16_bf16 v[64:79], v[106:109], v[98:101], v[64:79]
	ds_read_b128 v[98:101], v184 offset:57600
	ds_read_b128 v[102:105], v216 offset:12544
	ds_read_b128 v[106:109], v181
	s_waitcnt lgkmcnt(0)
	v_mfma_f32_32x32x16_bf16 v[80:95], v[98:101], v[106:109], v[80:95]
	v_mfma_f32_32x32x16_bf16 v[64:79], v[102:105], v[106:109], v[64:79]
	ds_read_b128 v[98:101], v192 offset:57600
	ds_read_b128 v[102:105], v208 offset:12544
	ds_read_b128 v[106:109], v181 offset:8192
	s_waitcnt lgkmcnt(0)
	v_mfma_f32_32x32x16_bf16 v[80:95], v[98:101], v[106:109], v[80:95]
	v_mfma_f32_32x32x16_bf16 v[64:79], v[102:105], v[106:109], v[64:79]
	ds_read_b128 v[98:101], v190 offset:57600
	ds_read_b128 v[102:105], v206 offset:12544
	ds_read_b128 v[106:109], v181 offset:16384
	s_waitcnt lgkmcnt(0)
	v_mfma_f32_32x32x16_bf16 v[80:95], v[98:101], v[106:109], v[80:95]
	v_mfma_f32_32x32x16_bf16 v[64:79], v[102:105], v[106:109], v[64:79]
	ds_read_b128 v[98:101], v173 offset:57600
	ds_read_b128 v[102:105], v202 offset:12544
	ds_read_b128 v[106:109], v181 offset:24576
	s_waitcnt lgkmcnt(0)
; #define SBAR() __builtin_amdgcn_sched_barrier(0)
; template <int D0> __device__ __forceinline__ void pv_one(f32x16& od, int vb, bf16x8 pa0, bf16x8 pa1, bf16x8 pa2, bf16x8 pa3) {
;     const s16x4 l0 = tr_read<v_rd_off(D0, 0, 0)>(vb), h0 = tr_read<v_rd_off(D0, 0, 1)>(vb), l1 = tr_read<v_rd_off(D0, 1, 0)>(vb), h1 = tr_read<v_rd_off(D0, 1, 1)>(vb);
;     const s16x4 l2 = tr_read<v_rd_off(D0, 2, 0)>(vb), h2 = tr_read<v_rd_off(D0, 2, 1)>(vb), l3 = tr_read<v_rd_off(D0, 3, 0)>(vb), h3 = tr_read<v_rd_off(D0, 3, 1)>(vb);
;     asm volatile("s_waitcnt lgkmcnt(0)" ::: "memory"); SBAR();
;     ...
;     od = __builtin_amdgcn_mfma_f32_32x32x16_bf16(pa0, PK(l0, h0), od, 0, 0, 0);
;     od = __builtin_amdgcn_mfma_f32_32x32x16_bf16(pa1, PK(l1, h1), od, 0, 0, 0);
;     od = __builtin_amdgcn_mfma_f32_32x32x16_bf16(pa2, PK(l2, h2), od, 0, 0, 0);
;     od = __builtin_amdgcn_mfma_f32_32x32x16_bf16(pa3, PK(l3, h3), od, 0, 0, 0);
;     ...
; }
; __device__ __forceinline__ void pv_d0(f32x16* o, int vb, bf16x8 pa0, bf16x8 pa1, bf16x8 pa2, bf16x8 pa3) {
;     pv_one<0>(o[0], vb, pa0, pa1, pa2, pa3); pv_one<1>(o[1], vb, pa0, pa1, pa2, pa3); pv_one<2>(o[2], vb, pa0, pa1, pa2, pa3); pv_one<3>(o[3], vb, pa0, pa1, pa2, pa3);
; __device__ __forceinline__ void partialSM(f32x16& p0, f32x16& p1, float& m_reg, float& mn, float& alpha, const float C, const float thr) {
;     float pmax = p0[0];
; #pragma unroll
;     for (int r = 1; r < 16; ++r) pmax = fmaxf(pmax, p0[r]);
; #pragma unroll
;     for (int r = 0; r < 16; ++r) pmax = fmaxf(pmax, p1[r]);
;     { auto rr = __builtin_amdgcn_permlane32_swap(__float_as_uint(pmax), __float_as_uint(pmax), false, false);
;       pmax = fmaxf(__uint_as_float(rr[0]), __uint_as_float(rr[1])); }
; __device__ __forceinline__ void finishSM(f32x16& p0, f32x16& p1, float alpha, float& l_reg, bf16x8& pa0, bf16x8& pa1, bf16x8& pa2, bf16x8& pa3) {
; #pragma unroll
;     for (int r = 0; r < 16; ++r) p1[r] = __builtin_amdgcn_exp2f(p1[r]);
;     float ps = 0;
; #pragma unroll
;     for (int r = 0; r < 16; ++r) ps += p0[r];
; #pragma unroll
;     for (int r = 0; r < 16; ++r) ps += p1[r];
;     { auto rr = __builtin_amdgcn_permlane32_swap(__float_as_uint(ps), __float_as_uint(ps), false, false);
;       ps = __uint_as_float(rr[0]) + __uint_as_float(rr[1]); }
;     l_reg = l_reg * alpha + ps;
;     ...
;     PK4(p0, 0, pa0); PK4(p0, 8, pa1); PK4(p1, 0, pa2); PK4(p1, 8, pa3);
;     ...
; }
	v_mfma_f32_32x32x16_bf16 v[80:95], v[98:101], v[106:109], v[80:95]
	v_add_f32_e32 v98, 0, v219
	v_add_f32_e32 v98, v221, v98
	v_add_f32_e32 v98, v157, v98
	v_add_f32_e32 v98, v220, v98
	v_add_f32_e32 v98, v156, v98
	v_add_f32_e32 v98, v218, v98
	v_add_f32_e32 v98, v154, v98
	v_add_f32_e32 v98, v155, v98
	v_add_f32_e32 v98, v151, v98
	v_add_f32_e32 v98, v153, v98
	v_add_f32_e32 v98, v150, v98
	v_add_f32_e32 v98, v152, v98
	v_mfma_f32_32x32x16_bf16 v[64:79], v[102:105], v[106:109], v[64:79]
	v_exp_f32_e32 v108, v142
	v_add_f32_e32 v98, v147, v98
	v_exp_f32_e32 v109, v143
	v_add_f32_e32 v98, v149, v98
	v_add_f32_e32 v98, v146, v98
	v_add_f32_e32 v98, v148, v98
	v_add_f32_e32 v98, v108, v98
	v_add_f32_e32 v98, v109, v98
	v_add_f32_e32 v98, v110, v98
	v_add_f32_e32 v98, v111, v98
	v_add_f32_e32 v98, v112, v98
	v_add_f32_e32 v98, v113, v98
	v_add_f32_e32 v98, v114, v98
	v_add_f32_e32 v98, v115, v98
	v_add_f32_e32 v98, v116, v98
	v_add_f32_e32 v98, v117, v98
	v_add_f32_e32 v98, v118, v98
	v_add_f32_e32 v98, v119, v98
	v_add_f32_e32 v98, v120, v98
	v_add_f32_e32 v98, v121, v98
	v_add_f32_e32 v98, v122, v98
	v_add_f32_e32 v102, v123, v98
	v_mov_b32_e32 v103, v102
	v_cvt_pk_bf16_f32 v98, v219, v221
	v_cvt_pk_bf16_f32 v99, v157, v220
	v_cvt_pk_bf16_f32 v100, v156, v218
	v_cvt_pk_bf16_f32 v101, v154, v155
	s_nop 1
	v_permlane32_swap_b32_e32 v102, v103
	v_permlane32_swap_b32_e32 v98, v100
	v_permlane32_swap_b32_e32 v99, v101
	v_cvt_pk_bf16_f32 v104, v151, v153
	v_cvt_pk_bf16_f32 v105, v150, v152
	v_cvt_pk_bf16_f32 v106, v147, v149
	v_cvt_pk_bf16_f32 v107, v146, v148
	v_cvt_pk_bf16_f32 v108, v108, v109
	v_cvt_pk_bf16_f32 v109, v110, v111
	v_cvt_pk_bf16_f32 v110, v112, v113
	v_cvt_pk_bf16_f32 v111, v114, v115
	v_cvt_pk_bf16_f32 v112, v116, v117
	v_cvt_pk_bf16_f32 v113, v118, v119
	v_cvt_pk_bf16_f32 v114, v120, v121
	v_cvt_pk_bf16_f32 v115, v122, v123
	s_nop 0
	v_permlane32_swap_b32_e32 v104, v106
	v_permlane32_swap_b32_e32 v105, v107
	v_permlane32_swap_b32_e32 v108, v110
	v_permlane32_swap_b32_e32 v109, v111
	v_permlane32_swap_b32_e32 v112, v114
	v_permlane32_swap_b32_e32 v113, v115
	ds_read_b64_tr_b16 v[116:117], v200 offset:0
	ds_read_b64_tr_b16 v[118:119], v200 offset:0x800
	ds_read_b64_tr_b16 v[120:121], v200 offset:0x1000
	ds_read_b64_tr_b16 v[122:123], v200 offset:0x1800
	ds_read_b64_tr_b16 v[124:125], v200 offset:0x2000
	ds_read_b64_tr_b16 v[126:127], v200 offset:0x2800
	ds_read_b64_tr_b16 v[128:129], v200 offset:0x3000
	ds_read_b64_tr_b16 v[130:131], v200 offset:0x3800
	s_waitcnt lgkmcnt(0)
	s_nop 0
	v_mfma_f32_32x32x16_bf16 v[48:63], v[98:101], v[116:119], v[48:63]
	ds_read_b64_tr_b16 v[116:117], v200 offset:0x200
	ds_read_b64_tr_b16 v[118:119], v200 offset:0xa00
	v_mfma_f32_32x32x16_bf16 v[48:63], v[104:107], v[120:123], v[48:63]
	ds_read_b64_tr_b16 v[120:121], v200 offset:0x1200
	ds_read_b64_tr_b16 v[122:123], v200 offset:0x1a00
	v_mfma_f32_32x32x16_bf16 v[48:63], v[108:111], v[124:127], v[48:63]
	ds_read_b64_tr_b16 v[124:125], v200 offset:0x2200
	ds_read_b64_tr_b16 v[126:127], v200 offset:0x2a00
	v_mfma_f32_32x32x16_bf16 v[48:63], v[112:115], v[128:131], v[48:63]
	ds_read_b64_tr_b16 v[128:129], v200 offset:0x3200
	ds_read_b64_tr_b16 v[130:131], v200 offset:0x3a00
	s_waitcnt lgkmcnt(0)
	v_mfma_f32_32x32x16_bf16 v[32:47], v[98:101], v[116:119], v[32:47]
	ds_read_b64_tr_b16 v[116:117], v200 offset:0x400
	ds_read_b64_tr_b16 v[118:119], v200 offset:0xc00
	v_mfma_f32_32x32x16_bf16 v[32:47], v[104:107], v[120:123], v[32:47]
	ds_read_b64_tr_b16 v[120:121], v200 offset:0x1400
	ds_read_b64_tr_b16 v[122:123], v200 offset:0x1c00
	v_mfma_f32_32x32x16_bf16 v[32:47], v[108:111], v[124:127], v[32:47]
	ds_read_b64_tr_b16 v[124:125], v200 offset:0x2400
	ds_read_b64_tr_b16 v[126:127], v200 offset:0x2c00
	v_mfma_f32_32x32x16_bf16 v[32:47], v[112:115], v[128:131], v[32:47]
	ds_read_b64_tr_b16 v[128:129], v200 offset:0x3400
	ds_read_b64_tr_b16 v[130:131], v200 offset:0x3c00
	s_waitcnt lgkmcnt(0)
	v_mfma_f32_32x32x16_bf16 v[16:31], v[98:101], v[116:119], v[16:31]
	ds_read_b64_tr_b16 v[116:117], v200 offset:0x600
	ds_read_b64_tr_b16 v[118:119], v200 offset:0xe00
	v_mfma_f32_32x32x16_bf16 v[16:31], v[104:107], v[120:123], v[16:31]
	ds_read_b64_tr_b16 v[120:121], v200 offset:0x1600
	ds_read_b64_tr_b16 v[122:123], v200 offset:0x1e00
	v_mfma_f32_32x32x16_bf16 v[16:31], v[108:111], v[124:127], v[16:31]
	ds_read_b64_tr_b16 v[124:125], v200 offset:0x2600
	ds_read_b64_tr_b16 v[126:127], v200 offset:0x2e00
	v_mfma_f32_32x32x16_bf16 v[16:31], v[112:115], v[128:131], v[16:31]
	ds_read_b64_tr_b16 v[128:129], v200 offset:0x3600
	ds_read_b64_tr_b16 v[130:131], v200 offset:0x3e00
	s_waitcnt lgkmcnt(0)
	v_mfma_f32_32x32x16_bf16 v[0:15], v[98:101], v[116:119], v[0:15]
	v_max_f32_e32 v98, v81, v81
	v_max_f32_e32 v99, v80, v80
	v_max_f32_e32 v98, v99, v98
	v_max3_f32 v98, v98, v82, v83
	v_max3_f32 v98, v98, v84, v85
	v_max3_f32 v98, v98, v86, v87
	v_max3_f32 v98, v98, v88, v89
	v_max3_f32 v98, v98, v90, v91
	v_max3_f32 v98, v98, v92, v93
	v_mfma_f32_32x32x16_bf16 v[0:15], v[104:107], v[120:123], v[0:15]
	v_max3_f32 v98, v98, v94, v95
	v_max3_f32 v98, v98, v64, v65
	v_max3_f32 v98, v98, v66, v67
	v_max3_f32 v98, v98, v68, v69
	v_max3_f32 v98, v98, v70, v71
	v_max3_f32 v98, v98, v72, v73
	v_max3_f32 v98, v98, v74, v75
	v_max3_f32 v98, v98, v76, v77
	v_mfma_f32_32x32x16_bf16 v[0:15], v[108:111], v[124:127], v[0:15]
	v_max3_f32 v98, v98, v78, v79
	v_mov_b32_e32 v99, v98
	s_nop 1
	v_permlane32_swap_b32_e32 v98, v99
	v_max_f32_e32 v99, v99, v99
	v_max_f32_e32 v98, v98, v98
	v_max_f32_e32 v98, v98, v99
	v_sub_f32_e32 v99, v98, v204
	v_cmp_ge_f32_e32 vcc, s72, v99
	v_max_f32_e32 v99, v204, v204
	v_max_f32_e32 v99, v99, v98
	v_mfma_f32_32x32x16_bf16 v[0:15], v[112:115], v[128:131], v[0:15]
	v_sub_f32_e32 v98, v204, v99
	v_mul_f32_e32 v98, 0x3dd53b94, v98
	v_exp_f32_e32 v98, v98
	s_cmp_eq_u64 vcc, exec
	s_cselect_b64 s[14:15], -1, 0
	v_cndmask_b32_e64 v98, v98, 1.0, s[14:15]
	v_cmp_gt_f32_e32 vcc, 1.0, v98
	s_barrier
; #define RESC(al) do { if (__any((al) < 1.f)) { if (hi == 0) al_l[r32] = (al); asm volatile("s_waitcnt lgkmcnt(0)" ::: "memory"); \
;     _Pragma("unroll") for (int d = 0; d < 4; ++d) _Pragma("unroll") for (int r = 0; r < 16; ++r) o[d][r] *= al_l[crow(r, hi)]; } } while (0)
; template <int DQK, int DK1, int LDQ, int LDK, int LDKR, int LDV, int NQL, int SDEPTH>
; __device__ __forceinline__ void attn_core(const AttnArgs& a, char* lds, f32x16 (&o)[4]) {
;     ...
;     __syncthreads(); RESC(alB);
	s_cbranch_vccz .LBB0_233
	s_and_saveexec_b64 s[20:21], s[12:13]
	s_movk_i32 s37, 0x7fff
	s_movk_i32 s73, 0x47ff
	v_readlane_b32 s68, v255, 18
	ds_write_b32 v165, v98 offset:128
	s_or_b64 exec, exec, s[20:21]
	s_waitcnt lgkmcnt(0)
	v_add_u32_e32 v100, v161, v96
	ds_read_b128 v[104:107], v100 offset:224
	ds_read_b128 v[108:111], v100 offset:192
	ds_read_b128 v[112:115], v100 offset:160
	ds_read_b128 v[116:119], v100 offset:128
	s_waitcnt lgkmcnt(3)
	v_pk_mul_f32 v[60:61], v[60:61], v[104:105]
	s_waitcnt lgkmcnt(2)
	v_pk_mul_f32 v[56:57], v[56:57], v[108:109]
	s_waitcnt lgkmcnt(1)
	v_pk_mul_f32 v[52:53], v[52:53], v[112:113]
	v_pk_mul_f32 v[62:63], v[62:63], v[106:107]
	v_pk_mul_f32 v[58:59], v[58:59], v[110:111]
	v_pk_mul_f32 v[54:55], v[54:55], v[114:115]
	s_waitcnt lgkmcnt(0)
	v_pk_mul_f32 v[50:51], v[50:51], v[118:119]
	v_pk_mul_f32 v[48:49], v[48:49], v[116:117]
	v_pk_mul_f32 v[44:45], v[44:45], v[104:105]
	v_pk_mul_f32 v[40:41], v[40:41], v[108:109]
	v_pk_mul_f32 v[36:37], v[36:37], v[112:113]
	v_pk_mul_f32 v[46:47], v[46:47], v[106:107]
	v_pk_mul_f32 v[42:43], v[42:43], v[110:111]
	v_pk_mul_f32 v[38:39], v[38:39], v[114:115]
	v_pk_mul_f32 v[34:35], v[34:35], v[118:119]
	v_pk_mul_f32 v[32:33], v[32:33], v[116:117]
	v_pk_mul_f32 v[28:29], v[28:29], v[104:105]
	v_pk_mul_f32 v[24:25], v[24:25], v[108:109]
	v_pk_mul_f32 v[20:21], v[20:21], v[112:113]
	v_pk_mul_f32 v[30:31], v[30:31], v[106:107]
	v_pk_mul_f32 v[26:27], v[26:27], v[110:111]
	v_pk_mul_f32 v[22:23], v[22:23], v[114:115]
	v_pk_mul_f32 v[18:19], v[18:19], v[118:119]
	v_pk_mul_f32 v[16:17], v[16:17], v[116:117]
	v_pk_mul_f32 v[12:13], v[12:13], v[104:105]
	v_pk_mul_f32 v[8:9], v[8:9], v[108:109]
	v_pk_mul_f32 v[4:5], v[4:5], v[112:113]
	v_pk_mul_f32 v[14:15], v[14:15], v[106:107]
	v_pk_mul_f32 v[10:11], v[10:11], v[110:111]
	v_pk_mul_f32 v[6:7], v[6:7], v[114:115]
	v_pk_mul_f32 v[2:3], v[2:3], v[118:119]
	v_pk_mul_f32 v[0:1], v[0:1], v[116:117]
	s_branch .LBB0_234
